# diff-attention DMA pieces re-spread (QK gaps 1,3,5,7 and PV gaps 0,2,4,6,8)
# speedup vs baseline: 1.0336x; 1.0044x over previous
; DI f32x16 mfma32(bf16x8 a, bf16x8 b, f32x16 c) { return __builtin_amdgcn_mfma_f32_32x32x16_bf16(a, b, c, 0, 0, 0); }
; #define SGB(mask, n) __builtin_amdgcn_sched_group_barrier(mask, n, 0)
; #define LDV(i_, hf_) do { VTR(vlo[(i_) % DV], (16 * (2 * (hf_) + ((i_) & 1))) * VSTR + 64 * ((i_) >> 1)); VTR(vhi[(i_) % DV], (16 * (2 * (hf_) + ((i_) & 1)) + 8) * VSTR + 64 * ((i_) >> 1)); } while (0)
; template <bool DIFF, bool NOMAX>
; DI void unit(LAS unsigned char* lds, const Tensors& Tn, int b, int hd, int qb) {
;     ...
; #pragma unroll
;                 for (int ks = 0; ks < NKS; ++ks) {
;                     sc = mfma32(kf[ks % DK], qf[ks], sc);
;                     if (ks + DK < NKS) kf[ks % DK] = LDK(hf, ks + DK);
;                 }
; #pragma unroll
;                 for (int ks = 0; ks < NKS; ++ks) { SGB(0x8, 1); if (ks + DK < NKS) SGB(0x100, 1); }
;                 __builtin_amdgcn_sched_barrier(0);
; #pragma unroll
;                 for (int i = 0; i < DV; ++i) LDV(i, hf);
.LBB0_800:
	s_waitcnt lgkmcnt(0)
	s_nop 0
	v_mfma_f32_32x32x16_bf16 v[132:147], v[192:195], v[148:151], v[132:147]
	ds_read_b128 v[192:195], v250 offset:128
	v_mfma_f32_32x32x16_bf16 v[132:147], v[188:191], v[152:155], v[132:147]
	s_and_b64 vcc, exec, s[74:75]
	s_cbranch_vccnz .Ldf_skip0
	s_andn2_b64 vcc, exec, s[6:7]
	s_cbranch_vccnz .Ldf_skip0
	s_add_i32 m0, s98, s50
	s_nop 0
	global_load_lds_dwordx4 v204, s[72:73]
.Ldf_skip0:
	ds_read_b128 v[188:191], v250 offset:160
	v_mfma_f32_32x32x16_bf16 v[132:147], v[184:187], v[156:159], v[132:147]
	ds_read_b128 v[184:187], v250 offset:192
	v_mfma_f32_32x32x16_bf16 v[132:147], v[180:183], v[160:163], v[132:147]
	s_and_b64 vcc, exec, s[74:75]
	s_cbranch_vccnz .Ldf_skip1
	s_andn2_b64 vcc, exec, s[56:57]
	s_cbranch_vccnz .Ldf_skip1
	s_add_i32 m0, s98, s26
	s_nop 0
	global_load_lds_dwordx4 v206, s[72:73]
.Ldf_skip1:
	ds_read_b128 v[180:183], v250 offset:224
	s_waitcnt lgkmcnt(0)
	v_mfma_f32_32x32x16_bf16 v[132:147], v[192:195], v[164:167], v[132:147]
	v_mfma_f32_32x32x16_bf16 v[132:147], v[188:191], v[168:171], v[132:147]
	s_and_b64 vcc, exec, s[74:75]
	s_cbranch_vccnz .Ldf_skip2
	s_andn2_b64 vcc, exec, s[58:59]
	s_cbranch_vccnz .Ldf_skip2
	s_add_i32 m0, s98, s27
	s_nop 0
	global_load_lds_dwordx4 v208, s[72:73]
.Ldf_skip2:
	v_mfma_f32_32x32x16_bf16 v[132:147], v[184:187], v[172:175], v[132:147]
	v_add_u32_e32 v184, s83, v245
	v_add3_u32 v249, v184, v246, s84
	v_mfma_f32_32x32x16_bf16 v[132:147], v[180:183], v[176:179], v[132:147]
	s_and_b64 vcc, exec, s[74:75]
	s_cbranch_vccnz .Ldf_skip3
	s_andn2_b64 vcc, exec, s[60:61]
	s_cbranch_vccnz .Ldf_skip3
	s_add_i32 m0, s98, s51
	s_nop 0
	global_load_lds_dwordx4 v210, s[72:73]

; DI float fast_exp2(float x) { return __builtin_amdgcn_exp2f(x); }
; DI f32x16 mfma32(bf16x8 a, bf16x8 b, f32x16 c) { return __builtin_amdgcn_mfma_f32_32x32x16_bf16(a, b, c, 0, 0, 0); }
; #define LDV(i_, hf_) do { VTR(vlo[(i_) % DV], (16 * (2 * (hf_) + ((i_) & 1))) * VSTR + 64 * ((i_) >> 1)); VTR(vhi[(i_) % DV], (16 * (2 * (hf_) + ((i_) & 1)) + 8) * VSTR + 64 * ((i_) >> 1)); } while (0)
; #define VWAIT(n_, a_, b_) asm volatile("s_waitcnt lgkmcnt(%c2)" : "+v"(a_), "+v"(b_) : "i"(n_) : "memory")
; template <bool DIFF, bool NOMAX>
; DI void unit(LAS unsigned char* lds, const Tensors& Tn, int b, int hd, int qb) {
;     ...
;                 f32x2_t ps2 = {0.f, 0.f};
; #pragma unroll
;                 for (int e = 0; e < 16; e += 2) { sc[e] = fast_exp2(sc[e]); sc[e + 1] = fast_exp2(sc[e + 1]); ps2 += (f32x2_t){sc[e], sc[e + 1]}; }
;                 lrow += ps2.x + ps2.y;
;                 bf16x8 pb[2]; pb[0] = pack8(sc, 0); pb[1] = pack8(sc, 1);
; #pragma unroll
;                 for (int i = 0; i < NPV; ++i) {
;                     VWAIT(2 * ((NPV - 1 - i) < (DV - 1) ? (NPV - 1 - i) : (DV - 1)), vlo[i % DV], vhi[i % DV]);
;                     const bf16x8 vf = __builtin_shufflevector(vlo[i % DV], vhi[i % DV], 0, 1, 2, 3, 4, 5, 6, 7);
;                     o[i >> 1] = mfma32(vf, pb[i & 1], o[i >> 1]);
;                     if (i + DV < NPV) LDV(i + DV, hf);
;                 }
.LBB0_802:
	s_waitcnt lgkmcnt(2)
	s_nop 7
	v_exp_f32_e32 v236, v132
	v_exp_f32_e32 v237, v133
	v_exp_f32_e32 v234, v134
	v_exp_f32_e32 v235, v135
	v_exp_f32_e32 v232, v136
	v_exp_f32_e32 v233, v137
	v_exp_f32_e32 v230, v138
	v_exp_f32_e32 v231, v139
	v_exp_f32_e32 v228, v140
	v_exp_f32_e32 v229, v141
	ds_read_b64_tr_b16 v[140:141], v249 offset:64
	v_exp_f32_e32 v226, v142
	v_exp_f32_e32 v227, v143
	ds_read_b64_tr_b16 v[142:143], v249 offset:4672
	s_waitcnt lgkmcnt(2)
	v_exp_f32_e32 v224, v144
	v_exp_f32_e32 v225, v145
	ds_read_b64_tr_b16 v[144:145], v249 offset:9280
	v_exp_f32_e32 v222, v146
	v_exp_f32_e32 v223, v147
	v_cvt_pk_bf16_f32 v132, v236, v237
	v_cvt_pk_bf16_f32 v133, v234, v235
	v_cvt_pk_bf16_f32 v134, v232, v233
	v_cvt_pk_bf16_f32 v135, v230, v231
	ds_read_b64_tr_b16 v[146:147], v249 offset:13888
	s_waitcnt lgkmcnt(2)
	v_cvt_pk_bf16_f32 v136, v228, v229
	v_cvt_pk_bf16_f32 v137, v226, v227
	v_mfma_f32_32x32x16_bf16 v[98:113], v[140:143], v[132:135], v[98:113]
	s_and_b64 vcc, exec, s[74:75]
	s_cbranch_vccnz .Ldf_skip4
	s_andn2_b64 vcc, exec, s[62:63]
	s_cbranch_vccnz .Ldf_skip4
	s_add_i32 m0, s98, s46
	s_nop 0
	global_load_lds_dwordx4 v212, s[72:73]
.Ldf_skip4:
	ds_read_b64_tr_b16 v[140:141], v249 offset:128
	ds_read_b64_tr_b16 v[142:143], v249 offset:4736
	v_cvt_pk_bf16_f32 v138, v224, v225
	v_cvt_pk_bf16_f32 v139, v222, v223
	s_waitcnt lgkmcnt(2)
	s_nop 1
	v_mfma_f32_32x32x16_bf16 v[98:113], v[144:147], v[136:139], v[98:113]
	ds_read_b64_tr_b16 v[144:145], v249 offset:9344
	ds_read_b64_tr_b16 v[146:147], v249 offset:13952
	s_waitcnt lgkmcnt(2)
	s_nop 0
	v_mfma_f32_32x32x16_bf16 v[82:97], v[140:143], v[132:135], v[82:97]
	s_and_b64 vcc, exec, s[74:75]
	s_cbranch_vccnz .Ldf_skip5
	s_andn2_b64 vcc, exec, s[64:65]
	s_cbranch_vccnz .Ldf_skip5
	s_add_i32 m0, s98, s47
	s_nop 0
	global_load_lds_dwordx4 v214, s[72:73]
.Ldf_skip5:
	ds_read_b64_tr_b16 v[140:141], v249 offset:192
	ds_read_b64_tr_b16 v[142:143], v249 offset:4800
	s_waitcnt lgkmcnt(2)
	s_nop 0
	v_mfma_f32_32x32x16_bf16 v[82:97], v[144:147], v[136:139], v[82:97]
	ds_read_b64_tr_b16 v[144:145], v249 offset:9408
	ds_read_b64_tr_b16 v[146:147], v249 offset:14016
	s_waitcnt lgkmcnt(2)
	s_nop 0
	v_mfma_f32_32x32x16_bf16 v[66:81], v[140:143], v[132:135], v[66:81]
	s_and_b64 vcc, exec, s[74:75]
	s_cbranch_vccnz .Ldf_skip6
	s_andn2_b64 vcc, exec, s[66:67]
	s_cbranch_vccnz .Ldf_skip6
	s_add_i32 m0, s98, s79
	s_nop 0
	global_load_lds_dwordx4 v216, s[72:73]
.Ldf_skip6:
	ds_read_b64_tr_b16 v[140:141], v249 offset:256
	ds_read_b64_tr_b16 v[142:143], v249 offset:4864
	s_waitcnt lgkmcnt(2)
	s_nop 0
	v_mfma_f32_32x32x16_bf16 v[66:81], v[144:147], v[136:139], v[66:81]
	ds_read_b64_tr_b16 v[144:145], v249 offset:9472
	ds_read_b64_tr_b16 v[146:147], v249 offset:14080
	s_waitcnt lgkmcnt(2)
	s_nop 0
	v_mfma_f32_32x32x16_bf16 v[50:65], v[140:143], v[132:135], v[50:65]
	s_and_b64 vcc, exec, s[74:75]
	s_cbranch_vccnz .Ldf_skip7
	s_andn2_b64 vcc, exec, s[68:69]
	s_cbranch_vccnz .Ldf_skip7
	s_add_i32 m0, s98, s80
	s_nop 0
	global_load_lds_dwordx4 v218, s[72:73]
.Ldf_skip7:
	ds_read_b64_tr_b16 v[140:141], v249 offset:320
	ds_read_b64_tr_b16 v[142:143], v249 offset:4928
	s_waitcnt lgkmcnt(2)
	s_nop 0
	v_mfma_f32_32x32x16_bf16 v[50:65], v[144:147], v[136:139], v[50:65]
	ds_read_b64_tr_b16 v[144:145], v249 offset:9536
	ds_read_b64_tr_b16 v[146:147], v249 offset:14144
	s_waitcnt lgkmcnt(2)
	s_nop 0
	v_mfma_f32_32x32x16_bf16 v[34:49], v[140:143], v[132:135], v[34:49]
	s_and_b64 vcc, exec, s[74:75]
	s_cbranch_vccnz .Ldf_skip8
	s_andn2_b64 vcc, exec, s[70:71]
	s_cbranch_vccnz .Ldf_skip8
	s_add_i32 m0, s98, s81
	s_nop 0
	global_load_lds_dwordx4 v220, s[72:73]
.Ldf_skip8:
	ds_read_b64_tr_b16 v[140:141], v249 offset:384
	ds_read_b64_tr_b16 v[142:143], v249 offset:4992
	s_waitcnt lgkmcnt(2)
	s_nop 0
	v_mfma_f32_32x32x16_bf16 v[34:49], v[144:147], v[136:139], v[34:49]
	ds_read_b64_tr_b16 v[144:145], v249 offset:9600
	ds_read_b64_tr_b16 v[146:147], v249 offset:14208
	s_waitcnt lgkmcnt(2)
	s_nop 0
	v_mfma_f32_32x32x16_bf16 v[18:33], v[140:143], v[132:135], v[18:33]
	ds_read_b64_tr_b16 v[140:141], v249 offset:448
	ds_read_b64_tr_b16 v[142:143], v249 offset:5056
	s_waitcnt lgkmcnt(2)
	s_nop 0
	v_mfma_f32_32x32x16_bf16 v[18:33], v[144:147], v[136:139], v[18:33]
	ds_read_b64_tr_b16 v[144:145], v249 offset:9664
	ds_read_b64_tr_b16 v[146:147], v249 offset:14272
	s_waitcnt lgkmcnt(2)
	s_nop 0
	s_waitcnt lgkmcnt(0)
	v_mfma_f32_32x32x16_bf16 v[114:129], v[184:187], v[132:135], v[114:129]
	v_mfma_f32_32x32x16_bf16 v[2:17], v[140:143], v[132:135], v[2:17]
	v_mfma_f32_32x32x16_bf16 v[114:129], v[180:183], v[136:139], v[114:129]
	v_mfma_f32_32x32x16_bf16 v[2:17], v[144:147], v[136:139], v[2:17]
	ds_read_b128 v[192:195], v250 offset:16896
	ds_read_b128 v[188:191], v250 offset:16928
	ds_read_b128 v[184:187], v250 offset:16960
	ds_read_b128 v[180:183], v250 offset:16992
	s_and_b64 vcc, exec, s[4:5]
	s_mov_b64 s[76:77], -1
	s_cbranch_vccnz .LBB0_804
	s_mov_b64 s[76:77], 0
